# weight conversion: the 32 folded-gain loads of w_uq/w_ukv items issued together after the weight loads instead of one vmcnt(0) ladder rung per element
# speedup vs baseline: 1.0032x; 1.0015x over previous
; #define LAS __attribute__((address_space(3)))
; __device__ __forceinline__ void transpose_item(const float* W, int K, int N, int NP, bf16* WT, LAS float* scr, int item, int lane, const LAS float* tab, long long* bias, int ldb, const float* kscale = nullptr) {
;     const int nblk = NP / 32, kb = item / nblk, nb = item - kb * nblk, k0 = 64 * kb, n0 = 32 * nb;
;     const int n = n0 + (lane & 31); const bool okn = n < N;
;     float wv_[32];
;     const float* wp = W + (size_t)(k0 + (lane >> 5)) * N + (okn ? n : 0);
; #pragma unroll
;     for (int i = 0; i < 32; ++i) wv_[i] = wp[(size_t)(2 * i) * N];
; #pragma unroll
;     for (int i = 0; i < 32; ++i) { if (!okn) wv_[i] = 0.f; if (kscale != nullptr) wv_[i] *= kscale[k0 + 2 * i + (lane >> 5)]; scr[(2 * i + (lane >> 5)) * 33 + (lane & 31)] = wv_[i]; }
; __device__ __forceinline__ void conv_CD(const ConvSrc s, const ConvDst d, int l, int worker, int nworkers, LAS float* scr, const LAS float* tab, long long* biasl, int lane) {
;     for (int it = worker; it < CV_IOUT + CV_IIN + CV_IUQ + CV_IUKV; it += nworkers) {
;         int r = it;
;         if (r < CV_IIN) { transpose_item(s.w_in + (size_t)l * DM * DIN, DM, DIN, DINP, d.win, scr, r, lane, tab, biasl, BIASW); continue; } r -= CV_IIN;
;         if (r < CV_IOUT) { transpose_item(s.w_out + (size_t)l * DM * DM, DM, DM, DM, d.wout, scr, r, lane, nullptr, nullptr, 0); continue; } r -= CV_IOUT;
;         if (r < CV_IUQ) { transpose_item(s.w_uq + (size_t)l * 512 * 768, 512, 768, 768, d.wuq, scr, r, lane, nullptr, nullptr, 0, s.g_q + l * 512); continue; } r -= CV_IUQ;
;         transpose_item(s.w_ukv + (size_t)l * 256 * 1024, 256, 1024, 1024, d.wukv, scr, r, lane, nullptr, nullptr, 0, s.g_kv + l * 256);
.LBB0_149:
	s_cmpk_gt_i32 s24, 0xeff
	s_mov_b64 s[4:5], -1
	s_cbranch_scc0 .LBB0_286
	s_cmpk_gt_u32 s24, 0x16ff
	s_cbranch_scc0 .LBB0_283
	s_cmpk_gt_u32 s24, 0x17bf
	s_cbranch_scc0 .LBB0_217
	s_lshl_b32 s4, s26, 5
	s_and_b32 s38, s4, 0xfffffc00
	s_lshl_b32 s4, s24, 1
	v_subrev_u32_e32 v1, s38, v57
	s_addk_i32 s4, 0xd080
	s_add_i32 s31, s27, s30
	s_and_b32 s56, s4, 0xffffffc0
	v_add_u32_e32 v1, s31, v1
	s_movk_i32 s4, 0x400
	v_or_b32_e32 v32, s56, v45
	v_cmp_gt_i32_e64 s[4:5], s4, v1
	v_lshlrev_b64 v[2:3], 12, v[32:33]
	v_lshl_add_u64 v[2:3], s[42:43], 0, v[2:3]
	v_cndmask_b32_e64 v4, 0, v1, s[4:5]
	v_ashrrev_i32_e32 v5, 31, v4
	v_lshl_add_u64 v[2:3], v[4:5], 2, v[2:3]
	v_add_co_u32_e32 v4, vcc, s93, v2
	s_movk_i32 s6, 0x4000
	s_nop 0
	v_addc_co_u32_e32 v5, vcc, 0, v3, vcc
	v_add_co_u32_e32 v6, vcc, s6, v2
	s_mov_b32 s6, 0x8000
	s_nop 0
	v_addc_co_u32_e32 v7, vcc, 0, v3, vcc
	v_add_co_u32_e32 v8, vcc, s75, v2
	v_cndmask_b32_e64 v1, 0, 1, s[8:9]
	s_nop 0
	v_addc_co_u32_e32 v9, vcc, 0, v3, vcc
	v_add_co_u32_e32 v10, vcc, s6, v2
	s_mov_b32 s6, 0xa000
	s_nop 0
	v_addc_co_u32_e32 v11, vcc, 0, v3, vcc
	v_add_co_u32_e32 v12, vcc, s6, v2
	s_mov_b32 s6, 0x14000
	s_nop 0
	v_addc_co_u32_e32 v13, vcc, 0, v3, vcc
	v_add_co_u32_e32 v14, vcc, s92, v2
	v_lshl_add_u64 v[42:43], v[32:33], 2, s[16:17]
	s_nop 0
	v_addc_co_u32_e32 v15, vcc, 0, v3, vcc
	v_add_co_u32_e32 v16, vcc, s80, v2
	s_nop 1
	v_addc_co_u32_e32 v17, vcc, 0, v3, vcc
	v_add_co_u32_e32 v18, vcc, s40, v2
	s_nop 1
	v_addc_co_u32_e32 v19, vcc, 0, v3, vcc
	v_add_co_u32_e32 v20, vcc, s13, v2
	s_nop 1
	v_addc_co_u32_e32 v21, vcc, 0, v3, vcc
	v_add_co_u32_e32 v22, vcc, s6, v2
	s_mov_b32 s6, 0x1a000
	s_nop 0
	v_addc_co_u32_e32 v23, vcc, 0, v3, vcc
	v_add_co_u32_e32 v24, vcc, s81, v2
	s_nop 1
	v_addc_co_u32_e32 v25, vcc, 0, v3, vcc
	v_add_co_u32_e32 v26, vcc, s41, v2
	s_nop 1
	v_addc_co_u32_e32 v27, vcc, 0, v3, vcc
	v_add_co_u32_e32 v28, vcc, s6, v2
	s_mov_b32 s6, 0x26000
	s_nop 0
	v_addc_co_u32_e32 v29, vcc, 0, v3, vcc
	v_add_co_u32_e32 v30, vcc, s15, v2
	s_nop 1
	v_addc_co_u32_e32 v31, vcc, 0, v3, vcc
	v_add_co_u32_e32 v66, vcc, s82, v2
	s_nop 1
	v_addc_co_u32_e32 v67, vcc, 0, v3, vcc
	v_add_co_u32_e32 v68, vcc, s78, v2
	s_nop 1
	v_addc_co_u32_e32 v69, vcc, 0, v3, vcc
	v_add_co_u32_e32 v70, vcc, s12, v2
	s_nop 1
	v_addc_co_u32_e32 v71, vcc, 0, v3, vcc
	v_add_co_u32_e32 v72, vcc, s72, v2
	s_nop 1
	v_addc_co_u32_e32 v73, vcc, 0, v3, vcc
	v_add_co_u32_e32 v74, vcc, s6, v2
	s_mov_b32 s6, 0x2c000
	s_nop 0
	v_addc_co_u32_e32 v75, vcc, 0, v3, vcc
	v_add_co_u32_e32 v76, vcc, s73, v2
	s_nop 1
	v_addc_co_u32_e32 v77, vcc, 0, v3, vcc
	v_add_co_u32_e32 v78, vcc, s83, v2
	s_nop 1
	v_addc_co_u32_e32 v79, vcc, 0, v3, vcc
	v_add_co_u32_e32 v80, vcc, s6, v2
	s_mov_b32 s6, 0x34000
	s_nop 0
	v_addc_co_u32_e32 v81, vcc, 0, v3, vcc
	v_add_co_u32_e32 v82, vcc, 0x2e000, v2
	s_nop 1
	v_addc_co_u32_e32 v83, vcc, 0, v3, vcc
	v_add_co_u32_e32 v84, vcc, s49, v2
	s_nop 1
	v_addc_co_u32_e32 v85, vcc, 0, v3, vcc
	v_add_co_u32_e32 v86, vcc, 0x32000, v2
	s_nop 1
	v_addc_co_u32_e32 v87, vcc, 0, v3, vcc
	v_add_co_u32_e32 v88, vcc, s6, v2
	v_cmp_ne_u32_e64 s[6:7], 1, v1
	s_nop 0
	v_addc_co_u32_e32 v89, vcc, 0, v3, vcc
	v_add_co_u32_e32 v90, vcc, 0x36000, v2
	s_nop 1
	v_addc_co_u32_e32 v91, vcc, 0, v3, vcc
	v_add_co_u32_e32 v92, vcc, 0x38000, v2
	s_nop 1
	v_addc_co_u32_e32 v93, vcc, 0, v3, vcc
	v_add_co_u32_e32 v94, vcc, 0x3a000, v2
	s_nop 1
	v_addc_co_u32_e32 v95, vcc, 0, v3, vcc
	v_add_co_u32_e32 v96, vcc, 0x3c000, v2
	s_nop 1
	v_addc_co_u32_e32 v97, vcc, 0, v3, vcc
	v_add_co_u32_e32 v98, vcc, 0x3e000, v2
	s_nop 1
	v_addc_co_u32_e32 v99, vcc, 0, v3, vcc
	global_load_dword v32, v[2:3], off
	global_load_dword v1, v[4:5], off
	s_nop 0
	global_load_dword v2, v[6:7], off
	global_load_dword v3, v[8:9], off
	global_load_dword v4, v[10:11], off
	global_load_dword v5, v[12:13], off
	s_nop 0
	global_load_dword v6, v[14:15], off
	global_load_dword v7, v[16:17], off
	global_load_dword v8, v[18:19], off
	global_load_dword v9, v[20:21], off
	global_load_dword v10, v[22:23], off
	global_load_dword v11, v[24:25], off
	global_load_dword v12, v[26:27], off
	global_load_dword v13, v[28:29], off
	global_load_dword v14, v[30:31], off
	global_load_dword v15, v[66:67], off
	global_load_dword v16, v[68:69], off
	global_load_dword v17, v[70:71], off
	global_load_dword v18, v[72:73], off
	global_load_dword v19, v[74:75], off
	global_load_dword v20, v[76:77], off
	global_load_dword v21, v[78:79], off
	global_load_dword v22, v[80:81], off
	global_load_dword v23, v[82:83], off
	global_load_dword v24, v[84:85], off
	global_load_dword v25, v[86:87], off
	global_load_dword v26, v[88:89], off
	global_load_dword v27, v[90:91], off
	global_load_dword v28, v[92:93], off
	global_load_dword v29, v[94:95], off
	global_load_dword v30, v[96:97], off
	global_load_dword v31, v[98:99], off
	s_andn2_b64 vcc, exec, s[8:9]
	s_cbranch_vccnz .Lks_skip0
	global_load_dword v66, v[42:43], off
	global_load_dword v67, v[42:43], off offset:8
	global_load_dword v68, v[42:43], off offset:16
	global_load_dword v69, v[42:43], off offset:24
	global_load_dword v70, v[42:43], off offset:32
	global_load_dword v71, v[42:43], off offset:40
	global_load_dword v72, v[42:43], off offset:48
	global_load_dword v73, v[42:43], off offset:56
	global_load_dword v74, v[42:43], off offset:64
	global_load_dword v75, v[42:43], off offset:72
	global_load_dword v76, v[42:43], off offset:80
	global_load_dword v77, v[42:43], off offset:88
	global_load_dword v78, v[42:43], off offset:96
	global_load_dword v79, v[42:43], off offset:104
	global_load_dword v80, v[42:43], off offset:112
	global_load_dword v81, v[42:43], off offset:120
	global_load_dword v82, v[42:43], off offset:128
	global_load_dword v83, v[42:43], off offset:136
	global_load_dword v84, v[42:43], off offset:144
	global_load_dword v85, v[42:43], off offset:152
	global_load_dword v86, v[42:43], off offset:160
	global_load_dword v87, v[42:43], off offset:168
	global_load_dword v88, v[42:43], off offset:176
	global_load_dword v89, v[42:43], off offset:184
	global_load_dword v90, v[42:43], off offset:192
	global_load_dword v91, v[42:43], off offset:200
	global_load_dword v92, v[42:43], off offset:208
	global_load_dword v93, v[42:43], off offset:216
	global_load_dword v94, v[42:43], off offset:224
	global_load_dword v95, v[42:43], off offset:232
	global_load_dword v96, v[42:43], off offset:240
	global_load_dword v97, v[42:43], off offset:248
; #define LAS __attribute__((address_space(3)))
; __device__ __forceinline__ void transpose_item(const float* W, int K, int N, int NP, bf16* WT, LAS float* scr, int item, int lane, const LAS float* tab, long long* bias, int ldb, const float* kscale = nullptr) {
;     const int nblk = NP / 32, kb = item / nblk, nb = item - kb * nblk, k0 = 64 * kb, n0 = 32 * nb;
;     const int n = n0 + (lane & 31); const bool okn = n < N;
;     float wv_[32];
;     const float* wp = W + (size_t)(k0 + (lane >> 5)) * N + (okn ? n : 0);
; #pragma unroll
;     for (int i = 0; i < 32; ++i) wv_[i] = wp[(size_t)(2 * i) * N];
; #pragma unroll
;     for (int i = 0; i < 32; ++i) { if (!okn) wv_[i] = 0.f; if (kscale != nullptr) wv_[i] *= kscale[k0 + 2 * i + (lane >> 5)]; scr[(2 * i + (lane >> 5)) * 33 + (lane & 31)] = wv_[i]; }
.Lks_skip0:
	s_andn2_b64 vcc, exec, s[8:9]
	s_waitcnt vmcnt(31)
	v_cndmask_b32_e64 v32, 0, v32, s[4:5]
	s_cbranch_vccnz .LBB0_154
	v_mul_f32_e32 v32, v32, v66
.LBB0_154:
	s_and_b64 vcc, exec, s[6:7]
	s_waitcnt vmcnt(30)
	v_cndmask_b32_e64 v1, 0, v1, s[4:5]
	ds_write_b32 v47, v32
	s_cbranch_vccnz .LBB0_156
	v_mul_f32_e32 v1, v1, v67
.LBB0_156:
	s_and_b64 vcc, exec, s[6:7]
	s_waitcnt vmcnt(29)
	v_cndmask_b32_e64 v2, 0, v2, s[4:5]
	ds_write_b32 v47, v1 offset:264
	s_cbranch_vccnz .LBB0_158
	v_mul_f32_e32 v2, v2, v68
.LBB0_158:
	s_and_b64 vcc, exec, s[6:7]
	s_waitcnt vmcnt(28)
	v_cndmask_b32_e64 v3, 0, v3, s[4:5]
	ds_write_b32 v47, v2 offset:528
	s_cbranch_vccnz .LBB0_160
	v_mul_f32_e32 v3, v3, v69
.LBB0_160:
	s_and_b64 vcc, exec, s[6:7]
	s_waitcnt vmcnt(27)
	v_cndmask_b32_e64 v4, 0, v4, s[4:5]
	ds_write_b32 v47, v3 offset:792
	s_cbranch_vccnz .LBB0_162
	v_mul_f32_e32 v4, v4, v70
.LBB0_162:
	s_and_b64 vcc, exec, s[6:7]
	s_waitcnt vmcnt(26)
	v_cndmask_b32_e64 v5, 0, v5, s[4:5]
	ds_write_b32 v47, v4 offset:1056
	s_cbranch_vccnz .LBB0_164
	v_mul_f32_e32 v5, v5, v71
.LBB0_164:
	s_and_b64 vcc, exec, s[6:7]
	s_waitcnt vmcnt(25)
	v_cndmask_b32_e64 v6, 0, v6, s[4:5]
	ds_write_b32 v47, v5 offset:1320
	s_cbranch_vccnz .LBB0_166
	v_mul_f32_e32 v6, v6, v72
.LBB0_166:
	s_and_b64 vcc, exec, s[6:7]
	s_waitcnt vmcnt(24)
	v_cndmask_b32_e64 v7, 0, v7, s[4:5]
	ds_write_b32 v47, v6 offset:1584
	s_cbranch_vccnz .LBB0_168
	v_mul_f32_e32 v7, v7, v73
.LBB0_168:
	s_and_b64 vcc, exec, s[6:7]
	s_waitcnt vmcnt(23)
	v_cndmask_b32_e64 v8, 0, v8, s[4:5]
	ds_write_b32 v47, v7 offset:1848
	s_cbranch_vccnz .LBB0_170
	v_mul_f32_e32 v8, v8, v74
.LBB0_170:
	s_and_b64 vcc, exec, s[6:7]
	s_waitcnt vmcnt(22)
	v_cndmask_b32_e64 v9, 0, v9, s[4:5]
	ds_write_b32 v47, v8 offset:2112
	s_cbranch_vccnz .LBB0_172
	v_mul_f32_e32 v9, v9, v75
.LBB0_172:
	s_and_b64 vcc, exec, s[6:7]
	s_waitcnt vmcnt(21)
	v_cndmask_b32_e64 v10, 0, v10, s[4:5]
	ds_write_b32 v47, v9 offset:2376
	s_cbranch_vccnz .LBB0_174
	v_mul_f32_e32 v10, v10, v76
.LBB0_174:
	s_and_b64 vcc, exec, s[6:7]
	s_waitcnt vmcnt(20)
	v_cndmask_b32_e64 v11, 0, v11, s[4:5]
	ds_write_b32 v47, v10 offset:2640
	s_cbranch_vccnz .LBB0_176
	v_mul_f32_e32 v11, v11, v77
.LBB0_176:
	s_and_b64 vcc, exec, s[6:7]
	s_waitcnt vmcnt(19)
	v_cndmask_b32_e64 v12, 0, v12, s[4:5]
	ds_write_b32 v47, v11 offset:2904
	s_cbranch_vccnz .LBB0_178
	v_mul_f32_e32 v12, v12, v78
.LBB0_178:
	s_and_b64 vcc, exec, s[6:7]
	s_waitcnt vmcnt(18)
	v_cndmask_b32_e64 v13, 0, v13, s[4:5]
	ds_write_b32 v47, v12 offset:3168
	s_cbranch_vccnz .LBB0_180
	v_mul_f32_e32 v13, v13, v79
.LBB0_180:
	s_and_b64 vcc, exec, s[6:7]
	s_waitcnt vmcnt(17)
	v_cndmask_b32_e64 v14, 0, v14, s[4:5]
	ds_write_b32 v47, v13 offset:3432
	s_cbranch_vccnz .LBB0_182
	v_mul_f32_e32 v14, v14, v80
.LBB0_182:
	s_and_b64 vcc, exec, s[6:7]
	s_waitcnt vmcnt(16)
	v_cndmask_b32_e64 v15, 0, v15, s[4:5]
	ds_write_b32 v47, v14 offset:3696
	s_cbranch_vccnz .LBB0_184
	v_mul_f32_e32 v15, v15, v81
.LBB0_184:
	s_and_b64 vcc, exec, s[6:7]
	s_waitcnt vmcnt(15)
	v_cndmask_b32_e64 v16, 0, v16, s[4:5]
	ds_write_b32 v47, v15 offset:3960
	s_cbranch_vccnz .LBB0_186
	v_mul_f32_e32 v16, v16, v82
.LBB0_186:
	s_and_b64 vcc, exec, s[6:7]
	s_waitcnt vmcnt(14)
	v_cndmask_b32_e64 v17, 0, v17, s[4:5]
	ds_write_b32 v47, v16 offset:4224
	s_cbranch_vccnz .LBB0_188
	v_mul_f32_e32 v17, v17, v83
.LBB0_188:
	s_and_b64 vcc, exec, s[6:7]
	s_waitcnt vmcnt(13)
	v_cndmask_b32_e64 v18, 0, v18, s[4:5]
	ds_write_b32 v47, v17 offset:4488
	s_cbranch_vccnz .LBB0_190
	v_mul_f32_e32 v18, v18, v84
.LBB0_190:
	s_and_b64 vcc, exec, s[6:7]
	s_waitcnt vmcnt(12)
	v_cndmask_b32_e64 v19, 0, v19, s[4:5]
	ds_write_b32 v47, v18 offset:4752
	s_cbranch_vccnz .LBB0_192
	v_mul_f32_e32 v19, v19, v85
.LBB0_192:
	s_and_b64 vcc, exec, s[6:7]
	s_waitcnt vmcnt(11)
	v_cndmask_b32_e64 v20, 0, v20, s[4:5]
	ds_write_b32 v47, v19 offset:5016
	s_cbranch_vccnz .LBB0_194
	v_mul_f32_e32 v20, v20, v86
.LBB0_194:
	s_and_b64 vcc, exec, s[6:7]
	s_waitcnt vmcnt(10)
	v_cndmask_b32_e64 v21, 0, v21, s[4:5]
	ds_write_b32 v47, v20 offset:5280
	s_cbranch_vccnz .LBB0_196
	v_mul_f32_e32 v21, v21, v87
.LBB0_196:
	s_and_b64 vcc, exec, s[6:7]
	s_waitcnt vmcnt(9)
	v_cndmask_b32_e64 v22, 0, v22, s[4:5]
	ds_write_b32 v47, v21 offset:5544
	s_cbranch_vccnz .LBB0_198
	v_mul_f32_e32 v22, v22, v88
.LBB0_198:
	s_and_b64 vcc, exec, s[6:7]
	s_waitcnt vmcnt(8)
	v_cndmask_b32_e64 v23, 0, v23, s[4:5]
	ds_write_b32 v47, v22 offset:5808
	s_cbranch_vccnz .LBB0_200
	v_mul_f32_e32 v23, v23, v89
.LBB0_200:
	s_and_b64 vcc, exec, s[6:7]
	s_waitcnt vmcnt(7)
	v_cndmask_b32_e64 v24, 0, v24, s[4:5]
	ds_write_b32 v47, v23 offset:6072
	s_cbranch_vccnz .LBB0_202
	v_mul_f32_e32 v24, v24, v90
.LBB0_202:
	s_and_b64 vcc, exec, s[6:7]
	s_waitcnt vmcnt(6)
	v_cndmask_b32_e64 v25, 0, v25, s[4:5]
	ds_write_b32 v47, v24 offset:6336
	s_cbranch_vccnz .LBB0_204
	v_mul_f32_e32 v25, v25, v91
.LBB0_204:
	s_and_b64 vcc, exec, s[6:7]
	s_waitcnt vmcnt(5)
	v_cndmask_b32_e64 v26, 0, v26, s[4:5]
	ds_write_b32 v47, v25 offset:6600
	s_cbranch_vccnz .LBB0_206
	v_mul_f32_e32 v26, v26, v92
.LBB0_206:
	s_and_b64 vcc, exec, s[6:7]
	s_waitcnt vmcnt(4)
	v_cndmask_b32_e64 v27, 0, v27, s[4:5]
	ds_write_b32 v47, v26 offset:6864
	s_cbranch_vccnz .LBB0_208
	v_mul_f32_e32 v27, v27, v93
.LBB0_208:
	s_and_b64 vcc, exec, s[6:7]
	s_waitcnt vmcnt(3)
	v_cndmask_b32_e64 v28, 0, v28, s[4:5]
	ds_write_b32 v47, v27 offset:7128
	s_cbranch_vccnz .LBB0_210
	v_mul_f32_e32 v28, v28, v94
.LBB0_210:
	s_and_b64 vcc, exec, s[6:7]
	s_waitcnt vmcnt(2)
	v_cndmask_b32_e64 v29, 0, v29, s[4:5]
	ds_write_b32 v47, v28 offset:7392
	s_cbranch_vccnz .LBB0_212
	v_mul_f32_e32 v29, v29, v95
.LBB0_212:
	s_and_b64 vcc, exec, s[6:7]
	s_waitcnt vmcnt(1)
	v_cndmask_b32_e64 v30, 0, v30, s[4:5]
	ds_write_b32 v47, v29 offset:7656
	s_cbranch_vccnz .LBB0_214
	v_mul_f32_e32 v30, v30, v96
.LBB0_214:
	s_and_b64 vcc, exec, s[6:7]
	s_waitcnt vmcnt(0)
	v_cndmask_b32_e64 v31, 0, v31, s[4:5]
	ds_write_b32 v47, v30 offset:7920
	s_cbranch_vccnz .LBB0_216
	v_mul_f32_e32 v31, v31, v97

; #define LAS __attribute__((address_space(3)))
; __device__ __forceinline__ void transpose_item(const float* W, int K, int N, int NP, bf16* WT, LAS float* scr, int item, int lane, const LAS float* tab, long long* bias, int ldb, const float* kscale = nullptr) {
;     const int nblk = NP / 32, kb = item / nblk, nb = item - kb * nblk, k0 = 64 * kb, n0 = 32 * nb;
;     const int n = n0 + (lane & 31); const bool okn = n < N;
;     float wv_[32];
;     const float* wp = W + (size_t)(k0 + (lane >> 5)) * N + (okn ? n : 0);
; #pragma unroll
;     for (int i = 0; i < 32; ++i) wv_[i] = wp[(size_t)(2 * i) * N];
; #pragma unroll
;     for (int i = 0; i < 32; ++i) { if (!okn) wv_[i] = 0.f; if (kscale != nullptr) wv_[i] *= kscale[k0 + 2 * i + (lane >> 5)]; scr[(2 * i + (lane >> 5)) * 33 + (lane & 31)] = wv_[i]; }
; __device__ __forceinline__ void conv_CD(const ConvSrc s, const ConvDst d, int l, int worker, int nworkers, LAS float* scr, const LAS float* tab, long long* biasl, int lane) {
;     ...
;         if (r < CV_IUQ) { transpose_item(s.w_uq + (size_t)l * 512 * 768, 512, 768, 768, d.wuq, scr, r, lane, nullptr, nullptr, 0, s.g_q + l * 512); continue; } r -= CV_IUQ;
.LBB0_217:
	s_and_b64 vcc, exec, s[4:5]
	s_cbranch_vccz .LBB0_297
	s_and_b32 s4, s25, 0xff
	s_mul_hi_u32 s38, s4, 0xaaaaaab
	s_and_b32 s4, s24, 0xff
	s_mulk_i32 s4, 0xab
	s_lshr_b32 s4, s4, 6
	s_and_b32 s39, s4, 0x3c0
	s_mulk_i32 s38, 0x300
	v_or_b32_e32 v32, s39, v45
	v_mov_b64_e32 v[2:3], s[18:19]
	s_movk_i32 s4, 0xc00
	v_subrev_u32_e32 v1, s38, v62
	s_add_i32 s31, s27, s30
	v_mad_u64_u32 v[2:3], s[4:5], v32, s4, v[2:3]
	v_add_u32_e32 v1, s31, v1
	s_movk_i32 s4, 0x300
	v_cmp_gt_i32_e64 s[4:5], s4, v1
	s_movk_i32 s6, 0x1000
	v_lshlrev_b32_e32 v42, 2, v32
	v_cndmask_b32_e64 v4, 0, v1, s[4:5]
	v_ashrrev_i32_e32 v5, 31, v4
	v_lshl_add_u64 v[2:3], v[4:5], 2, v[2:3]
	v_add_co_u32_e32 v4, vcc, s6, v2
	s_movk_i32 s6, 0x3000
	s_nop 0
	v_addc_co_u32_e32 v5, vcc, 0, v3, vcc
	v_add_co_u32_e32 v6, vcc, s6, v2
	s_movk_i32 s6, 0x4000
	s_nop 0
	v_addc_co_u32_e32 v7, vcc, 0, v3, vcc
	v_add_co_u32_e32 v8, vcc, s6, v2
	s_movk_i32 s6, 0x7000
	s_nop 0
	v_addc_co_u32_e32 v9, vcc, 0, v3, vcc
	v_add_co_u32_e32 v10, vcc, s75, v2
	v_cndmask_b32_e64 v1, 0, 1, s[10:11]
	s_nop 0
	v_addc_co_u32_e32 v11, vcc, 0, v3, vcc
	v_add_co_u32_e32 v12, vcc, s6, v2
	s_mov_b32 s6, 0x9000
	s_nop 0
	v_addc_co_u32_e32 v13, vcc, 0, v3, vcc
	v_add_co_u32_e32 v14, vcc, s6, v2
	s_mov_b32 s6, 0xa000
	s_nop 0
	v_addc_co_u32_e32 v15, vcc, 0, v3, vcc
	v_add_co_u32_e32 v16, vcc, s6, v2
	s_mov_b32 s6, 0xd000
	s_nop 0
	v_addc_co_u32_e32 v17, vcc, 0, v3, vcc
	v_add_co_u32_e32 v18, vcc, s92, v2
	s_nop 1
	v_addc_co_u32_e32 v19, vcc, 0, v3, vcc
	v_add_co_u32_e32 v20, vcc, s6, v2
	s_mov_b32 s6, 0xf000
	s_nop 0
	v_addc_co_u32_e32 v21, vcc, 0, v3, vcc
	v_add_co_u32_e32 v22, vcc, s6, v2
	s_mov_b32 s6, 0x13000
	s_nop 0
	v_addc_co_u32_e32 v23, vcc, 0, v3, vcc
	v_add_co_u32_e32 v24, vcc, s40, v2
	s_nop 1
	v_addc_co_u32_e32 v25, vcc, 0, v3, vcc
	v_add_co_u32_e32 v26, vcc, s13, v2
	s_nop 1
	v_addc_co_u32_e32 v27, vcc, 0, v3, vcc
	v_add_co_u32_e32 v28, vcc, s6, v2
	s_mov_b32 s6, 0x15000
	s_nop 0
	v_addc_co_u32_e32 v29, vcc, 0, v3, vcc
	v_add_co_u32_e32 v30, vcc, s6, v2
	s_mov_b32 s6, 0x19000
	s_nop 0
	v_addc_co_u32_e32 v31, vcc, 0, v3, vcc
	v_add_co_u32_e32 v66, vcc, s81, v2
	s_nop 1
	v_addc_co_u32_e32 v67, vcc, 0, v3, vcc
	v_add_co_u32_e32 v68, vcc, s41, v2
	s_nop 1
	v_addc_co_u32_e32 v69, vcc, 0, v3, vcc
	v_add_co_u32_e32 v70, vcc, s6, v2
	s_mov_b32 s6, 0x1b000
	s_nop 0
	v_addc_co_u32_e32 v71, vcc, 0, v3, vcc
	v_add_co_u32_e32 v72, vcc, s6, v2
	s_mov_b32 s6, 0x1f000
	s_nop 0
	v_addc_co_u32_e32 v73, vcc, 0, v3, vcc
	v_add_co_u32_e32 v74, vcc, s15, v2
	s_nop 1
	v_addc_co_u32_e32 v75, vcc, 0, v3, vcc
	v_add_co_u32_e32 v76, vcc, s82, v2
	s_nop 1
	v_addc_co_u32_e32 v77, vcc, 0, v3, vcc
	v_add_co_u32_e32 v78, vcc, s6, v2
	s_mov_b32 s6, 0x21000
	s_nop 0
	v_addc_co_u32_e32 v79, vcc, 0, v3, vcc
	v_add_co_u32_e32 v80, vcc, s6, v2
	s_mov_b32 s6, 0x25000
	s_nop 0
	v_addc_co_u32_e32 v81, vcc, 0, v3, vcc
	v_add_co_u32_e32 v82, vcc, s12, v2
	s_nop 1
	v_addc_co_u32_e32 v83, vcc, 0, v3, vcc
	v_add_co_u32_e32 v84, vcc, s72, v2
	s_nop 1
	v_addc_co_u32_e32 v85, vcc, 0, v3, vcc
	v_add_co_u32_e32 v86, vcc, s6, v2
	s_mov_b32 s6, 0x27000
	s_nop 0
	v_addc_co_u32_e32 v87, vcc, 0, v3, vcc
	v_add_co_u32_e32 v88, vcc, s6, v2
	v_cmp_ne_u32_e64 s[6:7], 1, v1
	s_nop 0
	v_addc_co_u32_e32 v89, vcc, 0, v3, vcc
	v_add_co_u32_e32 v90, vcc, s73, v2
	s_nop 1
	v_addc_co_u32_e32 v91, vcc, 0, v3, vcc
	v_add_co_u32_e32 v92, vcc, s83, v2
	s_nop 1
	v_addc_co_u32_e32 v93, vcc, 0, v3, vcc
	v_add_co_u32_e32 v94, vcc, 0x2b000, v2
	s_nop 1
	v_addc_co_u32_e32 v95, vcc, 0, v3, vcc
	v_add_co_u32_e32 v96, vcc, 0x2d000, v2
	s_nop 1
	v_addc_co_u32_e32 v97, vcc, 0, v3, vcc
	v_add_co_u32_e32 v98, vcc, 0x2e000, v2
	s_nop 1
	v_addc_co_u32_e32 v99, vcc, 0, v3, vcc
	global_load_dword v32, v[2:3], off
	global_load_dword v1, v[4:5], off offset:2048
	s_nop 0
	global_load_dword v2, v[6:7], off
	global_load_dword v3, v[8:9], off offset:2048
	global_load_dword v4, v[10:11], off
	global_load_dword v5, v[12:13], off offset:2048
	s_nop 0
	global_load_dword v6, v[14:15], off
	global_load_dword v7, v[16:17], off offset:2048
	global_load_dword v8, v[18:19], off
	global_load_dword v9, v[20:21], off offset:2048
	global_load_dword v10, v[22:23], off
	global_load_dword v11, v[24:25], off offset:2048
	global_load_dword v12, v[26:27], off
	global_load_dword v13, v[28:29], off offset:2048
	global_load_dword v14, v[30:31], off
	global_load_dword v15, v[66:67], off offset:2048
	global_load_dword v16, v[68:69], off
	global_load_dword v17, v[70:71], off offset:2048
	global_load_dword v18, v[72:73], off
	global_load_dword v19, v[74:75], off offset:2048
	global_load_dword v20, v[76:77], off
	global_load_dword v21, v[78:79], off offset:2048
	global_load_dword v22, v[80:81], off
	global_load_dword v23, v[82:83], off offset:2048
	global_load_dword v24, v[84:85], off
	global_load_dword v25, v[86:87], off offset:2048
	global_load_dword v26, v[88:89], off
	global_load_dword v27, v[90:91], off offset:2048
	global_load_dword v28, v[92:93], off
	global_load_dword v29, v[94:95], off offset:2048
	global_load_dword v30, v[96:97], off
	global_load_dword v31, v[98:99], off offset:2048
	s_andn2_b64 vcc, exec, s[10:11]
	s_cbranch_vccnz .Lks_skip1
	global_load_dword v66, v42, s[60:61]
	global_load_dword v67, v42, s[60:61] offset:8
	global_load_dword v68, v42, s[60:61] offset:16
	global_load_dword v69, v42, s[60:61] offset:24
	global_load_dword v70, v42, s[60:61] offset:32
	global_load_dword v71, v42, s[60:61] offset:40
	global_load_dword v72, v42, s[60:61] offset:48
	global_load_dword v73, v42, s[60:61] offset:56
	global_load_dword v74, v42, s[60:61] offset:64
	global_load_dword v75, v42, s[60:61] offset:72
	global_load_dword v76, v42, s[60:61] offset:80
	global_load_dword v77, v42, s[60:61] offset:88
	global_load_dword v78, v42, s[60:61] offset:96
	global_load_dword v79, v42, s[60:61] offset:104
	global_load_dword v80, v42, s[60:61] offset:112
	global_load_dword v81, v42, s[60:61] offset:120
	global_load_dword v82, v42, s[60:61] offset:128
	global_load_dword v83, v42, s[60:61] offset:136
	global_load_dword v84, v42, s[60:61] offset:144
	global_load_dword v85, v42, s[60:61] offset:152
	global_load_dword v86, v42, s[60:61] offset:160
	global_load_dword v87, v42, s[60:61] offset:168
	global_load_dword v88, v42, s[60:61] offset:176
	global_load_dword v89, v42, s[60:61] offset:184
	global_load_dword v90, v42, s[60:61] offset:192
	global_load_dword v91, v42, s[60:61] offset:200
	global_load_dword v92, v42, s[60:61] offset:208
	global_load_dword v93, v42, s[60:61] offset:216
	global_load_dword v94, v42, s[60:61] offset:224
	global_load_dword v95, v42, s[60:61] offset:232
	global_load_dword v96, v42, s[60:61] offset:240
	global_load_dword v97, v42, s[60:61] offset:248
.Lks_skip1:
	s_andn2_b64 vcc, exec, s[10:11]
	s_waitcnt vmcnt(31)
	v_cndmask_b32_e64 v32, 0, v32, s[4:5]
	s_cbranch_vccnz .LBB0_220
	v_mul_f32_e32 v32, v32, v66
